# weight-conversion tiles: the four row-group loads (and gain loads) issued together into distinct registers, one vmcnt wait, then the multiply + LDS-write groups
# speedup vs baseline: 1.0068x; 1.0068x over previous
.LBB0_67:
	s_or_b64 exec, exec, s[12:13]
	s_and_b64 vcc, exec, s[10:11]
	s_cbranch_vccnz .LBB0_69
	v_ashrrev_i32_e32 v9, 31, v8
	v_lshl_add_u64 v[40:41], v[8:9], 0, v[4:5]
	v_lshl_add_u64 v[40:41], v[40:41], 2, s[22:23]
	global_load_dword v44, v[40:41], off offset:64
	s_branch .LBB0_70
.LBB0_69:
	v_mov_b32_e32 v44, 1.0
.LBB0_70:
	v_mov_b32_e32 v40, 0
	v_mov_b32_e32 v41, 0
	v_mov_b32_e32 v42, 0
	v_mov_b32_e32 v43, 0
	s_and_saveexec_b64 s[12:13], s[8:9]
	s_cbranch_execz .LBB0_72
	v_add_u32_e32 v40, v8, v20
	v_mad_i64_i32 v[40:41], s[14:15], v40, s71, v[12:13]
	global_load_dwordx4 v[40:43], v[40:41], off
.LBB0_72:
	s_or_b64 exec, exec, s[12:13]
	s_and_b64 vcc, exec, s[10:11]
	s_cbranch_vccnz .LBB0_74
	v_ashrrev_i32_e32 v9, 31, v8
	v_lshl_add_u64 v[48:49], v[8:9], 0, v[4:5]
	v_lshl_add_u64 v[48:49], v[48:49], 2, s[22:23]
	global_load_dword v52, v[48:49], off offset:128
	s_branch .LBB0_75
.LBB0_74:
	v_mov_b32_e32 v52, 1.0
.LBB0_75:
	v_mov_b32_e32 v48, 0
	v_mov_b32_e32 v49, 0
	v_mov_b32_e32 v50, 0
	v_mov_b32_e32 v51, 0
	s_and_saveexec_b64 s[12:13], s[8:9]
	s_cbranch_execz .LBB0_77
	v_add_u32_e32 v48, v8, v22
	v_mad_i64_i32 v[48:49], s[14:15], v48, s71, v[12:13]
	global_load_dwordx4 v[48:51], v[48:49], off
.LBB0_77:
	s_or_b64 exec, exec, s[12:13]
	s_and_b64 vcc, exec, s[10:11]
	s_cbranch_vccnz .LBB0_79
	v_ashrrev_i32_e32 v9, 31, v8
	v_lshl_add_u64 v[56:57], v[8:9], 0, v[4:5]
	v_lshl_add_u64 v[56:57], v[56:57], 2, s[22:23]
	global_load_dword v60, v[56:57], off offset:192
	s_branch .LBB0_80
.LBB0_79:
	v_mov_b32_e32 v60, 1.0
.LBB0_80:
	v_mov_b32_e32 v56, 0
	v_mov_b32_e32 v57, 0
	v_mov_b32_e32 v58, 0
	v_mov_b32_e32 v59, 0
	s_and_saveexec_b64 s[10:11], s[8:9]
	s_cbranch_execz .LBB0_82
	v_add_u32_e32 v56, v8, v24
	v_mad_i64_i32 v[56:57], s[8:9], v56, s71, v[12:13]
	global_load_dwordx4 v[56:59], v[56:57], off
.LBB0_82:
	s_or_b64 exec, exec, s[10:11]
	s_waitcnt vmcnt(0)
	v_pk_mul_f32 v[0:1], v[14:15], v[0:1] op_sel_hi:[0,1]
	ds_write2_b32 v19, v0, v1 offset1:1
	v_pk_mul_f32 v[0:1], v[14:15], v[2:3] op_sel_hi:[0,1]
	ds_write2_b32 v19, v0, v1 offset0:2 offset1:3
	v_pk_mul_f32 v[40:41], v[44:45], v[40:41] op_sel_hi:[0,1]
	ds_write2_b32 v21, v40, v41 offset1:1
	v_pk_mul_f32 v[40:41], v[44:45], v[42:43] op_sel_hi:[0,1]
	ds_write2_b32 v21, v40, v41 offset0:2 offset1:3
	v_pk_mul_f32 v[48:49], v[52:53], v[48:49] op_sel_hi:[0,1]
	ds_write2_b32 v23, v48, v49 offset1:1
	v_pk_mul_f32 v[48:49], v[52:53], v[50:51] op_sel_hi:[0,1]
	ds_write2_b32 v23, v48, v49 offset0:2 offset1:3
	v_pk_mul_f32 v[56:57], v[60:61], v[56:57] op_sel_hi:[0,1]
	ds_write2_b32 v25, v56, v57 offset1:1
	v_pk_mul_f32 v[56:57], v[60:61], v[58:59] op_sel_hi:[0,1]
	ds_write2_b32 v25, v56, v57 offset0:2 offset1:3

.LBB0_99:
	s_or_b64 exec, exec, s[34:35]
	s_and_b64 vcc, exec, s[10:11]
	s_cbranch_vccnz .LBB0_101
	v_ashrrev_i32_e32 v9, 31, v8
	v_lshl_add_u64 v[40:41], v[8:9], 0, v[4:5]
	v_lshl_add_u64 v[40:41], v[40:41], 2, s[22:23]
	global_load_dword v44, v[40:41], off offset:64
	s_branch .LBB0_102

.LBB0_102:
	v_mov_b32_e32 v40, 0
	v_mov_b32_e32 v41, 0
	v_mov_b32_e32 v42, 0
	v_mov_b32_e32 v43, 0
	s_and_saveexec_b64 s[34:35], s[8:9]
	s_cbranch_execz .LBB0_104
	v_add_u32_e32 v40, v8, v20
	v_mad_i64_i32 v[40:41], s[36:37], v40, s71, v[12:13]
	global_load_dwordx4 v[40:43], v[40:41], off offset:1024
.LBB0_104:
	s_or_b64 exec, exec, s[34:35]
	s_and_b64 vcc, exec, s[10:11]
	s_cbranch_vccnz .LBB0_106
	v_ashrrev_i32_e32 v9, 31, v8
	v_lshl_add_u64 v[48:49], v[8:9], 0, v[4:5]
	v_lshl_add_u64 v[48:49], v[48:49], 2, s[22:23]
	global_load_dword v52, v[48:49], off offset:128
	s_branch .LBB0_107

.LBB0_107:
	v_mov_b32_e32 v48, 0
	v_mov_b32_e32 v49, 0
	v_mov_b32_e32 v50, 0
	v_mov_b32_e32 v51, 0
	s_and_saveexec_b64 s[34:35], s[8:9]
	s_cbranch_execz .LBB0_109
	v_add_u32_e32 v48, v8, v22
	v_mad_i64_i32 v[48:49], s[36:37], v48, s71, v[12:13]
	global_load_dwordx4 v[48:51], v[48:49], off offset:1024
.LBB0_109:
	s_or_b64 exec, exec, s[34:35]
	s_and_b64 vcc, exec, s[10:11]
	s_cbranch_vccnz .LBB0_111
	v_ashrrev_i32_e32 v9, 31, v8
	v_lshl_add_u64 v[56:57], v[8:9], 0, v[4:5]
	v_lshl_add_u64 v[56:57], v[56:57], 2, s[22:23]
	global_load_dword v60, v[56:57], off offset:192
	s_branch .LBB0_112

.LBB0_112:
	v_mov_b32_e32 v56, 0
	v_mov_b32_e32 v57, 0
	v_mov_b32_e32 v58, 0
	v_mov_b32_e32 v59, 0
	s_and_saveexec_b64 s[10:11], s[8:9]
	s_cbranch_execz .LBB0_114
	v_add_u32_e32 v56, v8, v24
	v_mad_i64_i32 v[56:57], s[8:9], v56, s71, v[12:13]
	global_load_dwordx4 v[56:59], v[56:57], off offset:1024

.LBB0_127:
	s_or_b64 exec, exec, s[36:37]
	s_and_b64 vcc, exec, s[12:13]
	v_ashrrev_i32_e32 v11, 31, v10
	s_cbranch_vccnz .LBB0_129
	v_lshl_add_u64 v[40:41], v[10:11], 0, v[4:5]
	v_lshl_add_u64 v[40:41], v[40:41], 2, s[22:23]
	global_load_dword v44, v[40:41], off offset:64
	s_branch .LBB0_130

.LBB0_130:
	v_mov_b32_e32 v40, 0
	v_mov_b32_e32 v41, 0
	v_mov_b32_e32 v42, 0
	v_mov_b32_e32 v43, 0
	s_and_saveexec_b64 s[36:37], s[6:7]
	s_cbranch_execz .LBB0_132
	v_add3_u32 v40, v4, v10, 16
	v_mad_i64_i32 v[40:41], s[38:39], v40, s71, v[6:7]
	global_load_dwordx4 v[40:43], v[40:41], off offset:1536
.LBB0_132:
	s_or_b64 exec, exec, s[36:37]
	s_and_b64 vcc, exec, s[12:13]
	s_cbranch_vccnz .LBB0_134
	v_lshl_add_u64 v[48:49], v[10:11], 0, v[4:5]
	v_lshl_add_u64 v[48:49], v[48:49], 2, s[22:23]
	global_load_dword v52, v[48:49], off offset:128
	s_branch .LBB0_135

.LBB0_135:
	v_mov_b32_e32 v48, 0
	v_mov_b32_e32 v49, 0
	v_mov_b32_e32 v50, 0
	v_mov_b32_e32 v51, 0
	s_and_saveexec_b64 s[36:37], s[6:7]
	s_cbranch_execz .LBB0_137
	v_add3_u32 v48, v4, v10, 32
	v_mad_i64_i32 v[48:49], s[38:39], v48, s71, v[6:7]
	global_load_dwordx4 v[48:51], v[48:49], off offset:1536
.LBB0_137:
	s_or_b64 exec, exec, s[36:37]
	s_and_b64 vcc, exec, s[12:13]
	s_cbranch_vccnz .LBB0_139
	v_lshl_add_u64 v[56:57], v[10:11], 0, v[4:5]
	v_lshl_add_u64 v[56:57], v[56:57], 2, s[22:23]
	global_load_dword v60, v[56:57], off offset:192
	s_branch .LBB0_140

.LBB0_140:
	v_mov_b32_e32 v56, 0
	v_mov_b32_e32 v57, 0
	v_mov_b32_e32 v58, 0
	v_mov_b32_e32 v59, 0
	s_and_saveexec_b64 s[12:13], s[6:7]
	s_cbranch_execz .LBB0_142
	v_add3_u32 v56, v4, v10, 48
	v_mad_i64_i32 v[56:57], s[36:37], v56, s71, v[6:7]
	global_load_dwordx4 v[56:59], v[56:57], off offset:1536
.LBB0_142:
	s_or_b64 exec, exec, s[12:13]
	s_orn2_b64 s[12:13], s[8:9], exec
	s_waitcnt vmcnt(0)
	v_pk_mul_f32 v[0:1], v[12:13], v[0:1] op_sel_hi:[0,1]
	ds_write2_b32 v16, v0, v1 offset1:1
	v_pk_mul_f32 v[0:1], v[12:13], v[2:3] op_sel_hi:[0,1]
	ds_write2_b32 v16, v0, v1 offset0:2 offset1:3
	v_pk_mul_f32 v[40:41], v[44:45], v[40:41] op_sel_hi:[0,1]
	ds_write2_b32 v17, v40, v41 offset1:1
	v_pk_mul_f32 v[40:41], v[44:45], v[42:43] op_sel_hi:[0,1]
	ds_write2_b32 v17, v40, v41 offset0:2 offset1:3
	v_pk_mul_f32 v[48:49], v[52:53], v[48:49] op_sel_hi:[0,1]
	ds_write2_b32 v18, v48, v49 offset1:1
	v_pk_mul_f32 v[48:49], v[52:53], v[50:51] op_sel_hi:[0,1]
	ds_write2_b32 v18, v48, v49 offset0:2 offset1:3
	v_pk_mul_f32 v[56:57], v[60:61], v[56:57] op_sel_hi:[0,1]
	ds_write2_b32 v19, v56, v57 offset1:1
	v_pk_mul_f32 v[56:57], v[60:61], v[58:59] op_sel_hi:[0,1]
	ds_write2_b32 v19, v56, v57 offset0:2 offset1:3

.LBB0_155:
	s_or_b64 exec, exec, s[34:35]
	s_and_b64 vcc, exec, s[12:13]
	v_ashrrev_i32_e32 v11, 31, v10
	s_cbranch_vccnz .LBB0_157
	v_lshl_add_u64 v[40:41], v[10:11], 0, v[4:5]
	v_lshl_add_u64 v[40:41], v[40:41], 2, s[22:23]
	global_load_dword v44, v[40:41], off offset:64
	s_branch .LBB0_158

.LBB0_158:
	v_mov_b32_e32 v40, 0
	v_mov_b32_e32 v41, 0
	v_mov_b32_e32 v42, 0
	v_mov_b32_e32 v43, 0
	s_and_saveexec_b64 s[34:35], s[6:7]
	s_cbranch_execz .LBB0_160
	v_add3_u32 v40, v4, v10, 16
	v_mad_i64_i32 v[40:41], s[36:37], v40, s71, v[6:7]
	global_load_dwordx4 v[40:43], v[40:41], off
.LBB0_160:
	s_or_b64 exec, exec, s[34:35]
	s_and_b64 vcc, exec, s[12:13]
	s_cbranch_vccnz .LBB0_162
	v_lshl_add_u64 v[48:49], v[10:11], 0, v[4:5]
	v_lshl_add_u64 v[48:49], v[48:49], 2, s[22:23]
	global_load_dword v52, v[48:49], off offset:128
	s_branch .LBB0_163

.LBB0_163:
	v_mov_b32_e32 v48, 0
	v_mov_b32_e32 v49, 0
	v_mov_b32_e32 v50, 0
	v_mov_b32_e32 v51, 0
	s_and_saveexec_b64 s[34:35], s[6:7]
	s_cbranch_execz .LBB0_165
	v_add3_u32 v48, v4, v10, 32
	v_mad_i64_i32 v[48:49], s[36:37], v48, s71, v[6:7]
	global_load_dwordx4 v[48:51], v[48:49], off
.LBB0_165:
	s_or_b64 exec, exec, s[34:35]
	s_and_b64 vcc, exec, s[12:13]
	s_cbranch_vccnz .LBB0_167
	v_lshl_add_u64 v[56:57], v[10:11], 0, v[4:5]
	v_lshl_add_u64 v[56:57], v[56:57], 2, s[22:23]
	global_load_dword v60, v[56:57], off offset:192
	s_branch .LBB0_168

.LBB0_168:
	v_mov_b32_e32 v56, 0
	v_mov_b32_e32 v57, 0
	v_mov_b32_e32 v58, 0
	v_mov_b32_e32 v59, 0
	s_and_saveexec_b64 s[12:13], s[6:7]
	s_cbranch_execz .LBB0_170
	v_add3_u32 v56, v4, v10, 48
	v_mad_i64_i32 v[56:57], s[34:35], v56, s71, v[6:7]
	global_load_dwordx4 v[56:59], v[56:57], off

.LBB0_186:
	s_or_b64 exec, exec, s[36:37]
	s_and_b64 vcc, exec, s[12:13]
	s_cbranch_vccnz .LBB0_188
	v_ashrrev_i32_e32 v9, 31, v8
	v_lshl_add_u64 v[40:41], v[8:9], 0, v[4:5]
	v_lshl_add_u64 v[40:41], v[40:41], 2, s[22:23]
	global_load_dword v44, v[40:41], off offset:64
	s_branch .LBB0_189

.LBB0_189:
	v_mov_b32_e32 v40, 0
	v_mov_b32_e32 v41, 0
	v_mov_b32_e32 v42, 0
	v_mov_b32_e32 v43, 0
	s_and_saveexec_b64 s[36:37], s[10:11]
	s_cbranch_execz .LBB0_191
	v_add_u32_e32 v40, v8, v20
	v_mad_i64_i32 v[40:41], s[38:39], v40, s71, v[12:13]
	global_load_dwordx4 v[40:43], v[40:41], off offset:1664
.LBB0_191:
	s_or_b64 exec, exec, s[36:37]
	s_and_b64 vcc, exec, s[12:13]
	s_cbranch_vccnz .LBB0_193
	v_ashrrev_i32_e32 v9, 31, v8
	v_lshl_add_u64 v[48:49], v[8:9], 0, v[4:5]
	v_lshl_add_u64 v[48:49], v[48:49], 2, s[22:23]
	global_load_dword v52, v[48:49], off offset:128
	s_branch .LBB0_194

.LBB0_194:
	v_mov_b32_e32 v48, 0
	v_mov_b32_e32 v49, 0
	v_mov_b32_e32 v50, 0
	v_mov_b32_e32 v51, 0
	s_and_saveexec_b64 s[36:37], s[10:11]
	s_cbranch_execz .LBB0_196
	v_add_u32_e32 v48, v8, v22
	v_mad_i64_i32 v[48:49], s[38:39], v48, s71, v[12:13]
	global_load_dwordx4 v[48:51], v[48:49], off offset:1664
.LBB0_196:
	s_or_b64 exec, exec, s[36:37]
	s_and_b64 vcc, exec, s[12:13]
	s_cbranch_vccnz .LBB0_198
	v_ashrrev_i32_e32 v9, 31, v8
	v_lshl_add_u64 v[56:57], v[8:9], 0, v[4:5]
	v_lshl_add_u64 v[56:57], v[56:57], 2, s[22:23]
	global_load_dword v60, v[56:57], off offset:192
	s_branch .LBB0_199

.LBB0_199:
	v_mov_b32_e32 v56, 0
	v_mov_b32_e32 v57, 0
	v_mov_b32_e32 v58, 0
	v_mov_b32_e32 v59, 0
	s_and_saveexec_b64 s[12:13], s[10:11]
	s_cbranch_execz .LBB0_201
	v_add_u32_e32 v56, v8, v24
	v_mad_i64_i32 v[56:57], s[10:11], v56, s71, v[12:13]
	global_load_dwordx4 v[56:59], v[56:57], off offset:1664
.LBB0_201:
	s_or_b64 exec, exec, s[12:13]
	s_waitcnt vmcnt(0)
	v_pk_mul_f32 v[0:1], v[14:15], v[0:1] op_sel_hi:[0,1]
	ds_write2_b32 v19, v0, v1 offset1:1
	v_pk_mul_f32 v[0:1], v[14:15], v[2:3] op_sel_hi:[0,1]
	ds_write2_b32 v19, v0, v1 offset0:2 offset1:3
	v_pk_mul_f32 v[40:41], v[44:45], v[40:41] op_sel_hi:[0,1]
	ds_write2_b32 v21, v40, v41 offset1:1
	v_pk_mul_f32 v[40:41], v[44:45], v[42:43] op_sel_hi:[0,1]
	ds_write2_b32 v21, v40, v41 offset0:2 offset1:3
	v_pk_mul_f32 v[48:49], v[52:53], v[48:49] op_sel_hi:[0,1]
	ds_write2_b32 v23, v48, v49 offset1:1
	v_pk_mul_f32 v[48:49], v[52:53], v[50:51] op_sel_hi:[0,1]
	ds_write2_b32 v23, v48, v49 offset0:2 offset1:3
	v_pk_mul_f32 v[56:57], v[60:61], v[56:57] op_sel_hi:[0,1]
	ds_write2_b32 v25, v56, v57 offset1:1
	v_pk_mul_f32 v[56:57], v[60:61], v[58:59] op_sel_hi:[0,1]
	ds_write2_b32 v25, v56, v57 offset0:2 offset1:3

.LBB0_221:
	v_mov_b32_e32 v40, 0
	v_mov_b32_e32 v41, 0
	v_mov_b32_e32 v42, 0
	v_mov_b32_e32 v43, 0
	s_and_saveexec_b64 s[36:37], s[10:11]
	s_cbranch_execz .LBB0_223
	v_add_u32_e32 v40, v8, v20
	v_mad_i64_i32 v[40:41], s[38:39], v40, s71, v[12:13]
	global_load_dwordx4 v[40:43], v[40:41], off offset:2688

.LBB0_226:
	v_mov_b32_e32 v48, 0
	v_mov_b32_e32 v49, 0
	v_mov_b32_e32 v50, 0
	v_mov_b32_e32 v51, 0
	s_and_saveexec_b64 s[36:37], s[10:11]
	s_cbranch_execz .LBB0_228
	v_add_u32_e32 v48, v8, v22
	v_mad_i64_i32 v[48:49], s[38:39], v48, s71, v[12:13]
	global_load_dwordx4 v[48:51], v[48:49], off offset:2688

.LBB0_231:
	v_mov_b32_e32 v56, 0
	v_mov_b32_e32 v57, 0
	v_mov_b32_e32 v58, 0
	v_mov_b32_e32 v59, 0
	s_and_saveexec_b64 s[12:13], s[10:11]
	s_cbranch_execz .LBB0_233
	v_add_u32_e32 v56, v8, v24
	v_mad_i64_i32 v[56:57], s[10:11], v56, s71, v[12:13]
	global_load_dwordx4 v[56:59], v[56:57], off offset:2688

.LBB0_250:
	s_or_b64 exec, exec, s[36:37]
	s_and_b64 vcc, exec, s[14:15]
	s_cbranch_vccnz .LBB0_252
	v_ashrrev_i32_e32 v9, 31, v8
	v_lshl_add_u64 v[40:41], v[8:9], 0, v[4:5]
	v_lshl_add_u64 v[40:41], v[40:41], 2, s[22:23]
	global_load_dword v44, v[40:41], off offset:64
	s_branch .LBB0_253

.LBB0_253:
	v_mov_b32_e32 v40, 0
	v_mov_b32_e32 v41, 0
	v_mov_b32_e32 v42, 0
	v_mov_b32_e32 v43, 0
	s_and_saveexec_b64 s[36:37], s[12:13]
	s_cbranch_execz .LBB0_255
	v_add_u32_e32 v40, v8, v20
	v_mad_i64_i32 v[40:41], s[38:39], v40, s71, v[12:13]
	global_load_dwordx4 v[40:43], v[40:41], off offset:3712
.LBB0_255:
	s_or_b64 exec, exec, s[36:37]
	s_and_b64 vcc, exec, s[14:15]
	s_cbranch_vccnz .LBB0_257
	v_ashrrev_i32_e32 v9, 31, v8
	v_lshl_add_u64 v[48:49], v[8:9], 0, v[4:5]
	v_lshl_add_u64 v[48:49], v[48:49], 2, s[22:23]
	global_load_dword v52, v[48:49], off offset:128
	s_branch .LBB0_258

.LBB0_258:
	v_mov_b32_e32 v48, 0
	v_mov_b32_e32 v49, 0
	v_mov_b32_e32 v50, 0
	v_mov_b32_e32 v51, 0
	s_and_saveexec_b64 s[36:37], s[12:13]
	s_cbranch_execz .LBB0_260
	v_add_u32_e32 v48, v8, v22
	v_mad_i64_i32 v[48:49], s[38:39], v48, s71, v[12:13]
	global_load_dwordx4 v[48:51], v[48:49], off offset:3712
.LBB0_260:
	s_or_b64 exec, exec, s[36:37]
	s_and_b64 vcc, exec, s[14:15]
	s_cbranch_vccnz .LBB0_262
	v_ashrrev_i32_e32 v9, 31, v8
	v_lshl_add_u64 v[56:57], v[8:9], 0, v[4:5]
	v_lshl_add_u64 v[56:57], v[56:57], 2, s[22:23]
	global_load_dword v60, v[56:57], off offset:192
	s_branch .LBB0_263

.LBB0_263:
	v_mov_b32_e32 v56, 0
	v_mov_b32_e32 v57, 0
	v_mov_b32_e32 v58, 0
	v_mov_b32_e32 v59, 0
	s_and_saveexec_b64 s[14:15], s[12:13]
	s_cbranch_execz .LBB0_265
	v_add_u32_e32 v56, v8, v24
	v_mad_i64_i32 v[56:57], s[12:13], v56, s71, v[12:13]
	global_load_dwordx4 v[56:59], v[56:57], off offset:3712
.LBB0_265:
	s_or_b64 exec, exec, s[14:15]
	s_waitcnt vmcnt(0)
	v_pk_mul_f32 v[0:1], v[14:15], v[0:1] op_sel_hi:[0,1]
	ds_write2_b32 v19, v0, v1 offset1:1
	v_pk_mul_f32 v[0:1], v[14:15], v[2:3] op_sel_hi:[0,1]
	ds_write2_b32 v19, v0, v1 offset0:2 offset1:3
	v_pk_mul_f32 v[40:41], v[44:45], v[40:41] op_sel_hi:[0,1]
	ds_write2_b32 v21, v40, v41 offset1:1
	v_pk_mul_f32 v[40:41], v[44:45], v[42:43] op_sel_hi:[0,1]
	ds_write2_b32 v21, v40, v41 offset0:2 offset1:3
	v_pk_mul_f32 v[48:49], v[52:53], v[48:49] op_sel_hi:[0,1]
	ds_write2_b32 v23, v48, v49 offset1:1
	v_pk_mul_f32 v[48:49], v[52:53], v[50:51] op_sel_hi:[0,1]
	ds_write2_b32 v23, v48, v49 offset0:2 offset1:3
	v_pk_mul_f32 v[56:57], v[60:61], v[56:57] op_sel_hi:[0,1]
	ds_write2_b32 v25, v56, v57 offset1:1
	v_pk_mul_f32 v[56:57], v[60:61], v[58:59] op_sel_hi:[0,1]
	ds_write2_b32 v25, v56, v57 offset0:2 offset1:3

.LBB0_285:
	v_mov_b32_e32 v40, 0
	v_mov_b32_e32 v41, 0
	v_mov_b32_e32 v42, 0
	v_mov_b32_e32 v43, 0
	s_and_saveexec_b64 s[36:37], s[12:13]
	s_cbranch_execz .LBB0_287
	v_add_u32_e32 v40, v8, v20
	v_mad_i64_i32 v[40:41], s[38:39], v40, s71, v[12:13]
	global_load_dwordx4 v[40:43], v[40:41], off

.LBB0_290:
	v_mov_b32_e32 v48, 0
	v_mov_b32_e32 v49, 0
	v_mov_b32_e32 v50, 0
	v_mov_b32_e32 v51, 0
	s_and_saveexec_b64 s[36:37], s[12:13]
	s_cbranch_execz .LBB0_292
	v_add_u32_e32 v48, v8, v22
	v_mad_i64_i32 v[48:49], s[38:39], v48, s71, v[12:13]
	global_load_dwordx4 v[48:51], v[48:49], off

.LBB0_295:
	v_mov_b32_e32 v56, 0
	v_mov_b32_e32 v57, 0
	v_mov_b32_e32 v58, 0
	v_mov_b32_e32 v59, 0
	s_and_saveexec_b64 s[14:15], s[12:13]
	s_cbranch_execz .LBB0_297
	v_add_u32_e32 v56, v8, v24
	v_mad_i64_i32 v[56:57], s[12:13], v56, s71, v[12:13]
	global_load_dwordx4 v[56:59], v[56:57], off

.LBB0_381:
	s_or_b64 exec, exec, s[38:39]
	s_and_b64 vcc, exec, s[14:15]
	s_cbranch_vccnz .LBB0_383
	v_ashrrev_i32_e32 v9, 31, v8
	v_lshl_add_u64 v[40:41], v[8:9], 0, v[4:5]
	v_lshl_add_u64 v[40:41], v[40:41], 2, s[30:31]
	global_load_dword v44, v[40:41], off offset:64
	s_branch .LBB0_384

.LBB0_384:
	v_mov_b32_e32 v40, 0
	v_mov_b32_e32 v41, 0
	v_mov_b32_e32 v42, 0
	v_mov_b32_e32 v43, 0
	s_and_saveexec_b64 s[38:39], s[12:13]
	s_cbranch_execz .LBB0_386
	v_add_u32_e32 v40, v8, v20
	v_mad_i64_i32 v[40:41], s[46:47], v40, s63, v[12:13]
	global_load_dwordx4 v[40:43], v[40:41], off
.LBB0_386:
	s_or_b64 exec, exec, s[38:39]
	s_and_b64 vcc, exec, s[14:15]
	s_cbranch_vccnz .LBB0_388
	v_ashrrev_i32_e32 v9, 31, v8
	v_lshl_add_u64 v[48:49], v[8:9], 0, v[4:5]
	v_lshl_add_u64 v[48:49], v[48:49], 2, s[30:31]
	global_load_dword v52, v[48:49], off offset:128
	s_branch .LBB0_389

.LBB0_389:
	v_mov_b32_e32 v48, 0
	v_mov_b32_e32 v49, 0
	v_mov_b32_e32 v50, 0
	v_mov_b32_e32 v51, 0
	s_and_saveexec_b64 s[38:39], s[12:13]
	s_cbranch_execz .LBB0_391
	v_add_u32_e32 v48, v8, v22
	v_mad_i64_i32 v[48:49], s[46:47], v48, s63, v[12:13]
	global_load_dwordx4 v[48:51], v[48:49], off
.LBB0_391:
	s_or_b64 exec, exec, s[38:39]
	s_and_b64 vcc, exec, s[14:15]
	s_cbranch_vccnz .LBB0_393
	v_ashrrev_i32_e32 v9, 31, v8
	v_lshl_add_u64 v[56:57], v[8:9], 0, v[4:5]
	v_lshl_add_u64 v[56:57], v[56:57], 2, s[30:31]
	global_load_dword v60, v[56:57], off offset:192
	s_branch .LBB0_394

.LBB0_394:
	v_mov_b32_e32 v56, 0
	v_mov_b32_e32 v57, 0
	v_mov_b32_e32 v58, 0
	v_mov_b32_e32 v59, 0
	s_and_saveexec_b64 s[14:15], s[12:13]
	s_cbranch_execz .LBB0_396
	v_add_u32_e32 v56, v8, v24
	v_mad_i64_i32 v[56:57], s[12:13], v56, s63, v[12:13]
	global_load_dwordx4 v[56:59], v[56:57], off

.LBB0_413:
	s_or_b64 exec, exec, s[36:37]
	s_and_b64 vcc, exec, s[12:13]
	s_cbranch_vccnz .LBB0_415
	v_ashrrev_i32_e32 v9, 31, v8
	v_lshl_add_u64 v[40:41], v[8:9], 0, v[4:5]
	v_lshl_add_u64 v[40:41], v[40:41], 2, s[14:15]
	global_load_dword v44, v[40:41], off offset:64
	s_branch .LBB0_416

.LBB0_416:
	v_mov_b32_e32 v40, 0
	v_mov_b32_e32 v41, 0
	v_mov_b32_e32 v42, 0
	v_mov_b32_e32 v43, 0
	s_and_saveexec_b64 s[36:37], s[10:11]
	s_cbranch_execz .LBB0_418
	v_add_u32_e32 v40, v8, v20
	v_ashrrev_i32_e32 v41, 31, v40
	v_lshlrev_b64 v[40:41], 12, v[40:41]
	v_lshl_add_u64 v[40:41], v[12:13], 0, v[40:41]
	global_load_dwordx4 v[40:43], v[40:41], off
.LBB0_418:
	s_or_b64 exec, exec, s[36:37]
	s_and_b64 vcc, exec, s[12:13]
	s_cbranch_vccnz .LBB0_420
	v_ashrrev_i32_e32 v9, 31, v8
	v_lshl_add_u64 v[48:49], v[8:9], 0, v[4:5]
	v_lshl_add_u64 v[48:49], v[48:49], 2, s[14:15]
	global_load_dword v52, v[48:49], off offset:128
	s_branch .LBB0_421

.LBB0_421:
	v_mov_b32_e32 v48, 0
	v_mov_b32_e32 v49, 0
	v_mov_b32_e32 v50, 0
	v_mov_b32_e32 v51, 0
	s_and_saveexec_b64 s[36:37], s[10:11]
	s_cbranch_execz .LBB0_423
	v_add_u32_e32 v48, v8, v22
	v_ashrrev_i32_e32 v49, 31, v48
	v_lshlrev_b64 v[48:49], 12, v[48:49]
	v_lshl_add_u64 v[48:49], v[12:13], 0, v[48:49]
	global_load_dwordx4 v[48:51], v[48:49], off
.LBB0_423:
	s_or_b64 exec, exec, s[36:37]
	s_and_b64 vcc, exec, s[12:13]
	s_cbranch_vccnz .LBB0_425
	v_ashrrev_i32_e32 v9, 31, v8
	v_lshl_add_u64 v[56:57], v[8:9], 0, v[4:5]
	v_lshl_add_u64 v[56:57], v[56:57], 2, s[14:15]
	global_load_dword v60, v[56:57], off offset:192
	s_branch .LBB0_426

.LBB0_426:
	v_mov_b32_e32 v56, 0
	v_mov_b32_e32 v57, 0
	v_mov_b32_e32 v58, 0
	v_mov_b32_e32 v59, 0
	s_and_saveexec_b64 s[12:13], s[10:11]
	s_cbranch_execz .LBB0_428
	v_add_u32_e32 v56, v8, v24
	v_ashrrev_i32_e32 v57, 31, v56
	v_lshlrev_b64 v[56:57], 12, v[56:57]
	v_lshl_add_u64 v[56:57], v[12:13], 0, v[56:57]
	global_load_dwordx4 v[56:59], v[56:57], off

.LBB0_445:
	s_or_b64 exec, exec, s[40:41]
	s_and_b64 vcc, exec, s[12:13]
	s_cbranch_vccnz .LBB0_447
	v_ashrrev_i32_e32 v9, 31, v8
	v_lshl_add_u64 v[40:41], v[8:9], 0, v[4:5]
	v_lshl_add_u64 v[40:41], v[40:41], 2, s[34:35]
	global_load_dword v44, v[40:41], off offset:64
	s_branch .LBB0_448

.LBB0_448:
	v_mov_b32_e32 v40, 0
	v_mov_b32_e32 v41, 0
	v_mov_b32_e32 v42, 0
	v_mov_b32_e32 v43, 0
	s_and_saveexec_b64 s[40:41], s[10:11]
	s_cbranch_execz .LBB0_450
	v_add_u32_e32 v40, v8, v20
	v_ashrrev_i32_e32 v41, 31, v40
	v_lshlrev_b64 v[40:41], 12, v[40:41]
	v_lshl_add_u64 v[40:41], v[12:13], 0, v[40:41]
	global_load_dwordx4 v[40:43], v[40:41], off
.LBB0_450:
	s_or_b64 exec, exec, s[40:41]
	s_and_b64 vcc, exec, s[12:13]
	s_cbranch_vccnz .LBB0_452
	v_ashrrev_i32_e32 v9, 31, v8
	v_lshl_add_u64 v[48:49], v[8:9], 0, v[4:5]
	v_lshl_add_u64 v[48:49], v[48:49], 2, s[34:35]
	global_load_dword v52, v[48:49], off offset:128
	s_branch .LBB0_453

.LBB0_453:
	v_mov_b32_e32 v48, 0
	v_mov_b32_e32 v49, 0
	v_mov_b32_e32 v50, 0
	v_mov_b32_e32 v51, 0
	s_and_saveexec_b64 s[40:41], s[10:11]
	s_cbranch_execz .LBB0_455
	v_add_u32_e32 v48, v8, v22
	v_ashrrev_i32_e32 v49, 31, v48
	v_lshlrev_b64 v[48:49], 12, v[48:49]
	v_lshl_add_u64 v[48:49], v[12:13], 0, v[48:49]
	global_load_dwordx4 v[48:51], v[48:49], off
.LBB0_455:
	s_or_b64 exec, exec, s[40:41]
	s_and_b64 vcc, exec, s[12:13]
	s_cbranch_vccnz .LBB0_457
	v_ashrrev_i32_e32 v9, 31, v8
	v_lshl_add_u64 v[56:57], v[8:9], 0, v[4:5]
	v_lshl_add_u64 v[56:57], v[56:57], 2, s[34:35]
	global_load_dword v60, v[56:57], off offset:192
	s_branch .LBB0_458

.LBB0_512:
	v_mov_b32_e32 v40, 0
	v_mov_b32_e32 v41, 0
	v_mov_b32_e32 v42, 0
	v_mov_b32_e32 v43, 0
	s_and_saveexec_b64 s[34:35], s[8:9]
	s_cbranch_execz .LBB0_514
	v_add_u32_e32 v40, v8, v20
	v_ashrrev_i32_e32 v41, 31, v40
	v_lshlrev_b64 v[40:41], 12, v[40:41]
	v_lshl_add_u64 v[40:41], v[12:13], 0, v[40:41]
	global_load_dwordx4 v[40:43], v[40:41], off

.LBB0_517:
	v_mov_b32_e32 v48, 0
	v_mov_b32_e32 v49, 0
	v_mov_b32_e32 v50, 0
	v_mov_b32_e32 v51, 0
	s_and_saveexec_b64 s[34:35], s[8:9]
	s_cbranch_execz .LBB0_519
	v_add_u32_e32 v48, v8, v22
	v_ashrrev_i32_e32 v49, 31, v48
	v_lshlrev_b64 v[48:49], 12, v[48:49]
	v_lshl_add_u64 v[48:49], v[12:13], 0, v[48:49]
	global_load_dwordx4 v[48:51], v[48:49], off

.LBB0_522:
	v_mov_b32_e32 v56, 0
	v_mov_b32_e32 v57, 0
	v_mov_b32_e32 v58, 0
	v_mov_b32_e32 v59, 0
	s_and_saveexec_b64 s[10:11], s[8:9]
	s_cbranch_execz .LBB0_524
	v_add_u32_e32 v56, v8, v24
	v_ashrrev_i32_e32 v57, 31, v56
	v_lshlrev_b64 v[56:57], 12, v[56:57]
	v_lshl_add_u64 v[56:57], v[12:13], 0, v[56:57]
	global_load_dwordx4 v[56:59], v[56:57], off

.LBB0_541:
	s_or_b64 exec, exec, s[38:39]
	s_and_b64 vcc, exec, s[10:11]
	s_cbranch_vccnz .LBB0_543
	v_ashrrev_i32_e32 v9, 31, v8
	v_lshl_add_u64 v[40:41], v[8:9], 0, v[4:5]
	v_lshl_add_u64 v[40:41], v[40:41], 2, s[2:3]
	global_load_dword v44, v[40:41], off offset:64
	s_branch .LBB0_544

.LBB0_544:
	v_mov_b32_e32 v40, 0
	v_mov_b32_e32 v41, 0
	v_mov_b32_e32 v42, 0
	v_mov_b32_e32 v43, 0
	s_and_saveexec_b64 s[38:39], s[8:9]
	s_cbranch_execz .LBB0_546
	v_add_u32_e32 v40, v8, v20
	v_ashrrev_i32_e32 v41, 31, v40
	v_lshlrev_b64 v[40:41], 12, v[40:41]
	v_lshl_add_u64 v[40:41], v[12:13], 0, v[40:41]
	global_load_dwordx4 v[40:43], v[40:41], off
.LBB0_546:
	s_or_b64 exec, exec, s[38:39]
	s_and_b64 vcc, exec, s[10:11]
	s_cbranch_vccnz .LBB0_548
	v_ashrrev_i32_e32 v9, 31, v8
	v_lshl_add_u64 v[48:49], v[8:9], 0, v[4:5]
	v_lshl_add_u64 v[48:49], v[48:49], 2, s[2:3]
	global_load_dword v52, v[48:49], off offset:128
	s_branch .LBB0_549

.LBB0_549:
	v_mov_b32_e32 v48, 0
	v_mov_b32_e32 v49, 0
	v_mov_b32_e32 v50, 0
	v_mov_b32_e32 v51, 0
	s_and_saveexec_b64 s[38:39], s[8:9]
	s_cbranch_execz .LBB0_551
	v_add_u32_e32 v48, v8, v22
	v_ashrrev_i32_e32 v49, 31, v48
	v_lshlrev_b64 v[48:49], 12, v[48:49]
	v_lshl_add_u64 v[48:49], v[12:13], 0, v[48:49]
	global_load_dwordx4 v[48:51], v[48:49], off
.LBB0_551:
	s_or_b64 exec, exec, s[38:39]
	s_and_b64 vcc, exec, s[10:11]
	s_cbranch_vccnz .LBB0_553
	v_ashrrev_i32_e32 v9, 31, v8
	v_lshl_add_u64 v[56:57], v[8:9], 0, v[4:5]
	v_lshl_add_u64 v[56:57], v[56:57], 2, s[2:3]
	global_load_dword v60, v[56:57], off offset:192
	s_branch .LBB0_554

.LBB0_574:
	s_or_b64 exec, exec, s[36:37]
	s_and_b64 vcc, exec, s[12:13]
	s_cbranch_vccnz .LBB0_576
	v_ashrrev_i32_e32 v9, 31, v8
	v_lshl_add_u64 v[40:41], v[8:9], 0, v[4:5]
	v_lshl_add_u64 v[40:41], v[40:41], 2, s[2:3]
	global_load_dword v44, v[40:41], off offset:64
	s_branch .LBB0_577

.LBB0_579:
	s_or_b64 exec, exec, s[36:37]
	s_and_b64 vcc, exec, s[12:13]
	s_cbranch_vccnz .LBB0_581
	v_ashrrev_i32_e32 v9, 31, v8
	v_lshl_add_u64 v[48:49], v[8:9], 0, v[4:5]
	v_lshl_add_u64 v[48:49], v[48:49], 2, s[2:3]
	global_load_dword v52, v[48:49], off offset:128
	s_branch .LBB0_582

.LBB0_584:
	s_or_b64 exec, exec, s[36:37]
	s_and_b64 vcc, exec, s[12:13]
	s_cbranch_vccnz .LBB0_586
	v_ashrrev_i32_e32 v9, 31, v8
	v_lshl_add_u64 v[56:57], v[8:9], 0, v[4:5]
	v_lshl_add_u64 v[56:57], v[56:57], 2, s[2:3]
	global_load_dword v60, v[56:57], off offset:192
	s_branch .LBB0_587

.LBB0_623:
	s_or_b64 exec, exec, s[36:37]
	s_and_b64 vcc, exec, s[10:11]
	s_cbranch_vccnz .LBB0_625
	v_ashrrev_i32_e32 v9, 31, v8
	v_lshl_add_u64 v[40:41], v[8:9], 0, v[4:5]
	v_lshl_add_u64 v[40:41], v[40:41], 2, s[22:23]
	global_load_dword v44, v[40:41], off offset:64
	s_branch .LBB0_626

.LBB0_626:
	v_mov_b32_e32 v40, 0
	v_mov_b32_e32 v41, 0
	v_mov_b32_e32 v42, 0
	v_mov_b32_e32 v43, 0
	s_and_saveexec_b64 s[36:37], s[8:9]
	s_cbranch_execz .LBB0_628
	v_add_u32_e32 v40, v8, v20
	v_ashrrev_i32_e32 v41, 31, v40
	v_lshlrev_b64 v[40:41], 14, v[40:41]
	v_lshl_add_u64 v[40:41], v[12:13], 0, v[40:41]
	global_load_dwordx4 v[40:43], v[40:41], off
.LBB0_628:
	s_or_b64 exec, exec, s[36:37]
	s_and_b64 vcc, exec, s[10:11]
	s_cbranch_vccnz .LBB0_630
	v_ashrrev_i32_e32 v9, 31, v8
	v_lshl_add_u64 v[48:49], v[8:9], 0, v[4:5]
	v_lshl_add_u64 v[48:49], v[48:49], 2, s[22:23]
	global_load_dword v52, v[48:49], off offset:128
	s_branch .LBB0_631

.LBB0_631:
	v_mov_b32_e32 v48, 0
	v_mov_b32_e32 v49, 0
	v_mov_b32_e32 v50, 0
	v_mov_b32_e32 v51, 0
	s_and_saveexec_b64 s[36:37], s[8:9]
	s_cbranch_execz .LBB0_633
	v_add_u32_e32 v48, v8, v22
	v_ashrrev_i32_e32 v49, 31, v48
	v_lshlrev_b64 v[48:49], 14, v[48:49]
	v_lshl_add_u64 v[48:49], v[12:13], 0, v[48:49]
	global_load_dwordx4 v[48:51], v[48:49], off
.LBB0_633:
	s_or_b64 exec, exec, s[36:37]
	s_and_b64 vcc, exec, s[10:11]
	s_cbranch_vccnz .LBB0_635
	v_ashrrev_i32_e32 v9, 31, v8
	v_lshl_add_u64 v[56:57], v[8:9], 0, v[4:5]
	v_lshl_add_u64 v[56:57], v[56:57], 2, s[22:23]
	global_load_dword v60, v[56:57], off offset:192
	s_branch .LBB0_636

.LBB0_636:
	v_mov_b32_e32 v56, 0
	v_mov_b32_e32 v57, 0
	v_mov_b32_e32 v58, 0
	v_mov_b32_e32 v59, 0
	s_and_saveexec_b64 s[10:11], s[8:9]
	s_cbranch_execz .LBB0_638
	v_add_u32_e32 v56, v8, v24
	v_ashrrev_i32_e32 v57, 31, v56
	v_lshlrev_b64 v[56:57], 14, v[56:57]
	v_lshl_add_u64 v[56:57], v[12:13], 0, v[56:57]
	global_load_dwordx4 v[56:59], v[56:57], off

.LBB0_1379:
	s_or_b64 exec, exec, s[14:15]
	s_and_b64 vcc, exec, s[10:11]
	s_cbranch_vccnz .LBB0_1381
	v_ashrrev_i32_e32 v9, 31, v8
	v_lshl_add_u64 v[40:41], v[8:9], 0, v[4:5]
	v_lshl_add_u64 v[40:41], v[40:41], 2, s[16:17]
	global_load_dword v44, v[40:41], off offset:64
	s_branch .LBB0_1382

.LBB0_1382:
	v_mov_b32_e32 v40, 0
	v_mov_b32_e32 v41, 0
	v_mov_b32_e32 v42, 0
	v_mov_b32_e32 v43, 0
	s_and_saveexec_b64 s[14:15], s[8:9]
	s_cbranch_execz .LBB0_1384
	v_add_u32_e32 v40, v8, v20
	v_mad_i64_i32 v[40:41], s[22:23], v40, s71, v[12:13]
	global_load_dwordx4 v[40:43], v[40:41], off
.LBB0_1384:
	s_or_b64 exec, exec, s[14:15]
	s_and_b64 vcc, exec, s[10:11]
	s_cbranch_vccnz .LBB0_1386
	v_ashrrev_i32_e32 v9, 31, v8
	v_lshl_add_u64 v[48:49], v[8:9], 0, v[4:5]
	v_lshl_add_u64 v[48:49], v[48:49], 2, s[16:17]
	global_load_dword v52, v[48:49], off offset:128
	s_branch .LBB0_1387

.LBB0_1387:
	v_mov_b32_e32 v48, 0
	v_mov_b32_e32 v49, 0
	v_mov_b32_e32 v50, 0
	v_mov_b32_e32 v51, 0
	s_and_saveexec_b64 s[14:15], s[8:9]
	s_cbranch_execz .LBB0_1389
	v_add_u32_e32 v48, v8, v22
	v_mad_i64_i32 v[48:49], s[22:23], v48, s71, v[12:13]
	global_load_dwordx4 v[48:51], v[48:49], off
.LBB0_1389:
	s_or_b64 exec, exec, s[14:15]
	s_and_b64 vcc, exec, s[10:11]
	s_cbranch_vccnz .LBB0_1391
	v_ashrrev_i32_e32 v9, 31, v8
	v_lshl_add_u64 v[56:57], v[8:9], 0, v[4:5]
	v_lshl_add_u64 v[56:57], v[56:57], 2, s[16:17]
	global_load_dword v60, v[56:57], off offset:192
	s_branch .LBB0_1392

.LBB0_1411:
	s_or_b64 exec, exec, s[22:23]
	s_and_b64 vcc, exec, s[10:11]
	s_cbranch_vccnz .LBB0_1413
	v_ashrrev_i32_e32 v9, 31, v8
	v_lshl_add_u64 v[40:41], v[8:9], 0, v[4:5]
	v_lshl_add_u64 v[40:41], v[40:41], 2, s[16:17]
	global_load_dword v44, v[40:41], off offset:64
	s_branch .LBB0_1414

.LBB0_1414:
	v_mov_b32_e32 v40, 0
	v_mov_b32_e32 v41, 0
	v_mov_b32_e32 v42, 0
	v_mov_b32_e32 v43, 0
	s_and_saveexec_b64 s[22:23], s[8:9]
	s_cbranch_execz .LBB0_1416
	v_add_u32_e32 v40, v8, v20
	v_mad_i64_i32 v[40:41], s[24:25], v40, s71, v[12:13]
	global_load_dwordx4 v[40:43], v[40:41], off offset:1024
.LBB0_1416:
	s_or_b64 exec, exec, s[22:23]
	s_and_b64 vcc, exec, s[10:11]
	s_cbranch_vccnz .LBB0_1418
	v_ashrrev_i32_e32 v9, 31, v8
	v_lshl_add_u64 v[48:49], v[8:9], 0, v[4:5]
	v_lshl_add_u64 v[48:49], v[48:49], 2, s[16:17]
	global_load_dword v52, v[48:49], off offset:128
	s_branch .LBB0_1419

.LBB0_1419:
	v_mov_b32_e32 v48, 0
	v_mov_b32_e32 v49, 0
	v_mov_b32_e32 v50, 0
	v_mov_b32_e32 v51, 0
	s_and_saveexec_b64 s[22:23], s[8:9]
	s_cbranch_execz .LBB0_1421
	v_add_u32_e32 v48, v8, v22
	v_mad_i64_i32 v[48:49], s[24:25], v48, s71, v[12:13]
	global_load_dwordx4 v[48:51], v[48:49], off offset:1024
.LBB0_1421:
	s_or_b64 exec, exec, s[22:23]
	s_and_b64 vcc, exec, s[10:11]
	s_cbranch_vccnz .LBB0_1423
	v_ashrrev_i32_e32 v9, 31, v8
	v_lshl_add_u64 v[56:57], v[8:9], 0, v[4:5]
	v_lshl_add_u64 v[56:57], v[56:57], 2, s[16:17]
	global_load_dword v60, v[56:57], off offset:192
	s_branch .LBB0_1424

.LBB0_1439:
	s_or_b64 exec, exec, s[24:25]
	s_and_b64 vcc, exec, s[12:13]
	v_ashrrev_i32_e32 v11, 31, v10
	s_cbranch_vccnz .LBB0_1441
	v_lshl_add_u64 v[40:41], v[10:11], 0, v[4:5]
	v_lshl_add_u64 v[40:41], v[40:41], 2, s[16:17]
	global_load_dword v44, v[40:41], off offset:64
	s_branch .LBB0_1442

.LBB0_1442:
	v_mov_b32_e32 v40, 0
	v_mov_b32_e32 v41, 0
	v_mov_b32_e32 v42, 0
	v_mov_b32_e32 v43, 0
	s_and_saveexec_b64 s[24:25], s[6:7]
	s_cbranch_execz .LBB0_1444
	v_add3_u32 v40, v4, v10, 16
	v_mad_i64_i32 v[40:41], s[34:35], v40, s71, v[6:7]
	global_load_dwordx4 v[40:43], v[40:41], off offset:1536
.LBB0_1444:
	s_or_b64 exec, exec, s[24:25]
	s_and_b64 vcc, exec, s[12:13]
	s_cbranch_vccnz .LBB0_1446
	v_lshl_add_u64 v[48:49], v[10:11], 0, v[4:5]
	v_lshl_add_u64 v[48:49], v[48:49], 2, s[16:17]
	global_load_dword v52, v[48:49], off offset:128
	s_branch .LBB0_1447

.LBB0_1447:
	v_mov_b32_e32 v48, 0
	v_mov_b32_e32 v49, 0
	v_mov_b32_e32 v50, 0
	v_mov_b32_e32 v51, 0
	s_and_saveexec_b64 s[24:25], s[6:7]
	s_cbranch_execz .LBB0_1449
	v_add3_u32 v48, v4, v10, 32
	v_mad_i64_i32 v[48:49], s[34:35], v48, s71, v[6:7]
	global_load_dwordx4 v[48:51], v[48:49], off offset:1536
.LBB0_1449:
	s_or_b64 exec, exec, s[24:25]
	s_and_b64 vcc, exec, s[12:13]
	s_cbranch_vccnz .LBB0_1451
	v_lshl_add_u64 v[56:57], v[10:11], 0, v[4:5]
	v_lshl_add_u64 v[56:57], v[56:57], 2, s[16:17]
	global_load_dword v60, v[56:57], off offset:192
	s_branch .LBB0_1452

.LBB0_1452:
	v_mov_b32_e32 v56, 0
	v_mov_b32_e32 v57, 0
	v_mov_b32_e32 v58, 0
	v_mov_b32_e32 v59, 0
	s_and_saveexec_b64 s[12:13], s[6:7]
	s_cbranch_execz .LBB0_1454
	v_add3_u32 v56, v4, v10, 48
	v_mad_i64_i32 v[56:57], s[24:25], v56, s71, v[6:7]
	global_load_dwordx4 v[56:59], v[56:57], off offset:1536

.LBB0_1467:
	s_or_b64 exec, exec, s[22:23]
	s_and_b64 vcc, exec, s[12:13]
	v_ashrrev_i32_e32 v11, 31, v10
	s_cbranch_vccnz .LBB0_1469
	v_lshl_add_u64 v[40:41], v[10:11], 0, v[4:5]
	v_lshl_add_u64 v[40:41], v[40:41], 2, s[16:17]
	global_load_dword v44, v[40:41], off offset:64
	s_branch .LBB0_1470

.LBB0_1470:
	v_mov_b32_e32 v40, 0
	v_mov_b32_e32 v41, 0
	v_mov_b32_e32 v42, 0
	v_mov_b32_e32 v43, 0
	s_and_saveexec_b64 s[22:23], s[6:7]
	s_cbranch_execz .LBB0_1472
	v_add3_u32 v40, v4, v10, 16
	v_mad_i64_i32 v[40:41], s[34:35], v40, s71, v[6:7]
	global_load_dwordx4 v[40:43], v[40:41], off
.LBB0_1472:
	s_or_b64 exec, exec, s[22:23]
	s_and_b64 vcc, exec, s[12:13]
	s_cbranch_vccnz .LBB0_1474
	v_lshl_add_u64 v[48:49], v[10:11], 0, v[4:5]
	v_lshl_add_u64 v[48:49], v[48:49], 2, s[16:17]
	global_load_dword v52, v[48:49], off offset:128
	s_branch .LBB0_1475

.LBB0_1475:
	v_mov_b32_e32 v48, 0
	v_mov_b32_e32 v49, 0
	v_mov_b32_e32 v50, 0
	v_mov_b32_e32 v51, 0
	s_and_saveexec_b64 s[22:23], s[6:7]
	s_cbranch_execz .LBB0_1477
	v_add3_u32 v48, v4, v10, 32
	v_mad_i64_i32 v[48:49], s[34:35], v48, s71, v[6:7]
	global_load_dwordx4 v[48:51], v[48:49], off
.LBB0_1477:
	s_or_b64 exec, exec, s[22:23]
	s_and_b64 vcc, exec, s[12:13]
	s_cbranch_vccnz .LBB0_1479
	v_lshl_add_u64 v[56:57], v[10:11], 0, v[4:5]
	v_lshl_add_u64 v[56:57], v[56:57], 2, s[16:17]
	global_load_dword v60, v[56:57], off offset:192
	s_branch .LBB0_1480

.LBB0_1480:
	v_mov_b32_e32 v56, 0
	v_mov_b32_e32 v57, 0
	v_mov_b32_e32 v58, 0
	v_mov_b32_e32 v59, 0
	s_and_saveexec_b64 s[12:13], s[6:7]
	s_cbranch_execz .LBB0_1482
	v_add3_u32 v56, v4, v10, 48
	v_mad_i64_i32 v[56:57], s[22:23], v56, s71, v[6:7]
	global_load_dwordx4 v[56:59], v[56:57], off

.LBB0_1498:
	s_or_b64 exec, exec, s[22:23]
	s_and_b64 vcc, exec, s[12:13]
	s_cbranch_vccnz .LBB0_1500
	v_ashrrev_i32_e32 v9, 31, v8
	v_lshl_add_u64 v[40:41], v[8:9], 0, v[4:5]
	v_lshl_add_u64 v[40:41], v[40:41], 2, s[16:17]
	global_load_dword v44, v[40:41], off offset:64
	s_branch .LBB0_1501

.LBB0_1501:
	v_mov_b32_e32 v40, 0
	v_mov_b32_e32 v41, 0
	v_mov_b32_e32 v42, 0
	v_mov_b32_e32 v43, 0
	s_and_saveexec_b64 s[22:23], s[10:11]
	s_cbranch_execz .LBB0_1503
	v_add_u32_e32 v40, v8, v20
	v_mad_i64_i32 v[40:41], s[24:25], v40, s71, v[12:13]
	global_load_dwordx4 v[40:43], v[40:41], off offset:1664
.LBB0_1503:
	s_or_b64 exec, exec, s[22:23]
	s_and_b64 vcc, exec, s[12:13]
	s_cbranch_vccnz .LBB0_1505
	v_ashrrev_i32_e32 v9, 31, v8
	v_lshl_add_u64 v[48:49], v[8:9], 0, v[4:5]
	v_lshl_add_u64 v[48:49], v[48:49], 2, s[16:17]
	global_load_dword v52, v[48:49], off offset:128
	s_branch .LBB0_1506

.LBB0_1506:
	v_mov_b32_e32 v48, 0
	v_mov_b32_e32 v49, 0
	v_mov_b32_e32 v50, 0
	v_mov_b32_e32 v51, 0
	s_and_saveexec_b64 s[22:23], s[10:11]
	s_cbranch_execz .LBB0_1508
	v_add_u32_e32 v48, v8, v22
	v_mad_i64_i32 v[48:49], s[24:25], v48, s71, v[12:13]
	global_load_dwordx4 v[48:51], v[48:49], off offset:1664
.LBB0_1508:
	s_or_b64 exec, exec, s[22:23]
	s_and_b64 vcc, exec, s[12:13]
	s_cbranch_vccnz .LBB0_1510
	v_ashrrev_i32_e32 v9, 31, v8
	v_lshl_add_u64 v[56:57], v[8:9], 0, v[4:5]
	v_lshl_add_u64 v[56:57], v[56:57], 2, s[16:17]
	global_load_dword v60, v[56:57], off offset:192
	s_branch .LBB0_1511

.LBB0_1533:
	v_mov_b32_e32 v40, 0
	v_mov_b32_e32 v41, 0
	v_mov_b32_e32 v42, 0
	v_mov_b32_e32 v43, 0
	s_and_saveexec_b64 s[22:23], s[10:11]
	s_cbranch_execz .LBB0_1535
	v_add_u32_e32 v40, v8, v20
	v_mad_i64_i32 v[40:41], s[24:25], v40, s71, v[12:13]
	global_load_dwordx4 v[40:43], v[40:41], off offset:2688

.LBB0_1538:
	v_mov_b32_e32 v48, 0
	v_mov_b32_e32 v49, 0
	v_mov_b32_e32 v50, 0
	v_mov_b32_e32 v51, 0
	s_and_saveexec_b64 s[22:23], s[10:11]
	s_cbranch_execz .LBB0_1540
	v_add_u32_e32 v48, v8, v22
	v_mad_i64_i32 v[48:49], s[24:25], v48, s71, v[12:13]
	global_load_dwordx4 v[48:51], v[48:49], off offset:2688

.LBB0_1562:
	s_or_b64 exec, exec, s[22:23]
	s_and_b64 vcc, exec, s[14:15]
	s_cbranch_vccnz .LBB0_1564
	v_ashrrev_i32_e32 v9, 31, v8
	v_lshl_add_u64 v[40:41], v[8:9], 0, v[4:5]
	v_lshl_add_u64 v[40:41], v[40:41], 2, s[16:17]
	global_load_dword v44, v[40:41], off offset:64
	s_branch .LBB0_1565

.LBB0_1565:
	v_mov_b32_e32 v40, 0
	v_mov_b32_e32 v41, 0
	v_mov_b32_e32 v42, 0
	v_mov_b32_e32 v43, 0
	s_and_saveexec_b64 s[22:23], s[12:13]
	s_cbranch_execz .LBB0_1567
	v_add_u32_e32 v40, v8, v20
	v_mad_i64_i32 v[40:41], s[24:25], v40, s71, v[12:13]
	global_load_dwordx4 v[40:43], v[40:41], off offset:3712
.LBB0_1567:
	s_or_b64 exec, exec, s[22:23]
	s_and_b64 vcc, exec, s[14:15]
	s_cbranch_vccnz .LBB0_1569
	v_ashrrev_i32_e32 v9, 31, v8
	v_lshl_add_u64 v[48:49], v[8:9], 0, v[4:5]
	v_lshl_add_u64 v[48:49], v[48:49], 2, s[16:17]
	global_load_dword v52, v[48:49], off offset:128
	s_branch .LBB0_1570

.LBB0_1570:
	v_mov_b32_e32 v48, 0
	v_mov_b32_e32 v49, 0
	v_mov_b32_e32 v50, 0
	v_mov_b32_e32 v51, 0
	s_and_saveexec_b64 s[22:23], s[12:13]
	s_cbranch_execz .LBB0_1572
	v_add_u32_e32 v48, v8, v22
	v_mad_i64_i32 v[48:49], s[24:25], v48, s71, v[12:13]
	global_load_dwordx4 v[48:51], v[48:49], off offset:3712
.LBB0_1572:
	s_or_b64 exec, exec, s[22:23]
	s_and_b64 vcc, exec, s[14:15]
	s_cbranch_vccnz .LBB0_1574
	v_ashrrev_i32_e32 v9, 31, v8
	v_lshl_add_u64 v[56:57], v[8:9], 0, v[4:5]
	v_lshl_add_u64 v[56:57], v[56:57], 2, s[16:17]
	global_load_dword v60, v[56:57], off offset:192
	s_branch .LBB0_1575

.LBB0_1597:
	v_mov_b32_e32 v40, 0
	v_mov_b32_e32 v41, 0
	v_mov_b32_e32 v42, 0
	v_mov_b32_e32 v43, 0
	s_and_saveexec_b64 s[22:23], s[12:13]
	s_cbranch_execz .LBB0_1599
	v_add_u32_e32 v40, v8, v20
	v_mad_i64_i32 v[40:41], s[24:25], v40, s71, v[12:13]
	global_load_dwordx4 v[40:43], v[40:41], off

.LBB0_1602:
	v_mov_b32_e32 v48, 0
	v_mov_b32_e32 v49, 0
	v_mov_b32_e32 v50, 0
	v_mov_b32_e32 v51, 0
	s_and_saveexec_b64 s[22:23], s[12:13]
	s_cbranch_execz .LBB0_1604
	v_add_u32_e32 v48, v8, v22
	v_mad_i64_i32 v[48:49], s[24:25], v48, s71, v[12:13]
	global_load_dwordx4 v[48:51], v[48:49], off

.LBB0_1658:
	s_or_b64 exec, exec, s[20:21]
	s_and_b64 vcc, exec, s[14:15]
	s_cbranch_vccnz .LBB0_1660
	v_ashrrev_i32_e32 v9, 31, v8
	v_lshl_add_u64 v[40:41], v[8:9], 0, v[4:5]
	v_lshl_add_u64 v[40:41], v[40:41], 2, s[16:17]
	global_load_dword v44, v[40:41], off offset:64
	s_branch .LBB0_1661

.LBB0_1661:
	v_mov_b32_e32 v40, 0
	v_mov_b32_e32 v41, 0
	v_mov_b32_e32 v42, 0
	v_mov_b32_e32 v43, 0
	s_and_saveexec_b64 s[20:21], s[12:13]
	s_cbranch_execz .LBB0_1663
	v_add_u32_e32 v40, v8, v20
	v_mad_i64_i32 v[40:41], s[22:23], v40, s71, v[12:13]
	global_load_dwordx4 v[40:43], v[40:41], off
.LBB0_1663:
	s_or_b64 exec, exec, s[20:21]
	s_and_b64 vcc, exec, s[14:15]
	s_cbranch_vccnz .LBB0_1665
	v_ashrrev_i32_e32 v9, 31, v8
	v_lshl_add_u64 v[48:49], v[8:9], 0, v[4:5]
	v_lshl_add_u64 v[48:49], v[48:49], 2, s[16:17]
	global_load_dword v52, v[48:49], off offset:128
	s_branch .LBB0_1666

.LBB0_1666:
	v_mov_b32_e32 v48, 0
	v_mov_b32_e32 v49, 0
	v_mov_b32_e32 v50, 0
	v_mov_b32_e32 v51, 0
	s_and_saveexec_b64 s[20:21], s[12:13]
	s_cbranch_execz .LBB0_1668
	v_add_u32_e32 v48, v8, v22
	v_mad_i64_i32 v[48:49], s[22:23], v48, s71, v[12:13]
	global_load_dwordx4 v[48:51], v[48:49], off
.LBB0_1668:
	s_or_b64 exec, exec, s[20:21]
	s_and_b64 vcc, exec, s[14:15]
	s_cbranch_vccnz .LBB0_1670
	v_ashrrev_i32_e32 v9, 31, v8
	v_lshl_add_u64 v[56:57], v[8:9], 0, v[4:5]
	v_lshl_add_u64 v[56:57], v[56:57], 2, s[16:17]
	global_load_dword v60, v[56:57], off offset:192
	s_branch .LBB0_1671

.LBB0_1693:
	s_or_b64 exec, exec, s[20:21]
	s_and_b64 vcc, exec, s[14:15]
	s_cbranch_vccnz .LBB0_1695
	v_ashrrev_i32_e32 v9, 31, v8
	v_lshl_add_u64 v[40:41], v[8:9], 0, v[4:5]
	v_lshl_add_u64 v[40:41], v[40:41], 2, s[2:3]
	global_load_dword v44, v[40:41], off offset:64
	s_branch .LBB0_1696

.LBB0_1696:
	v_mov_b32_e32 v40, 0
	v_mov_b32_e32 v41, 0
	v_mov_b32_e32 v42, 0
	v_mov_b32_e32 v43, 0
	s_and_saveexec_b64 s[20:21], s[12:13]
	s_cbranch_execz .LBB0_1698
	v_add_u32_e32 v40, v8, v20
	v_mad_i64_i32 v[40:41], s[22:23], v40, s38, v[12:13]
	global_load_dwordx4 v[40:43], v[40:41], off
.LBB0_1698:
	s_or_b64 exec, exec, s[20:21]
	s_and_b64 vcc, exec, s[14:15]
	s_cbranch_vccnz .LBB0_1700
	v_ashrrev_i32_e32 v9, 31, v8
	v_lshl_add_u64 v[48:49], v[8:9], 0, v[4:5]
	v_lshl_add_u64 v[48:49], v[48:49], 2, s[2:3]
	global_load_dword v52, v[48:49], off offset:128
	s_branch .LBB0_1701

.LBB0_1701:
	v_mov_b32_e32 v48, 0
	v_mov_b32_e32 v49, 0
	v_mov_b32_e32 v50, 0
	v_mov_b32_e32 v51, 0
	s_and_saveexec_b64 s[20:21], s[12:13]
	s_cbranch_execz .LBB0_1703
	v_add_u32_e32 v48, v8, v22
	v_mad_i64_i32 v[48:49], s[22:23], v48, s38, v[12:13]
	global_load_dwordx4 v[48:51], v[48:49], off
.LBB0_1703:
	s_or_b64 exec, exec, s[20:21]
	s_and_b64 vcc, exec, s[14:15]
	s_cbranch_vccnz .LBB0_1705
	v_ashrrev_i32_e32 v9, 31, v8
	v_lshl_add_u64 v[56:57], v[8:9], 0, v[4:5]
	v_lshl_add_u64 v[56:57], v[56:57], 2, s[2:3]
	global_load_dword v60, v[56:57], off offset:192
	s_branch .LBB0_1706

.LBB0_1706:
	v_mov_b32_e32 v56, 0
	v_mov_b32_e32 v57, 0
	v_mov_b32_e32 v58, 0
	v_mov_b32_e32 v59, 0
	s_and_saveexec_b64 s[14:15], s[12:13]
	s_cbranch_execz .LBB0_1708
	v_add_u32_e32 v56, v8, v24
	v_mad_i64_i32 v[56:57], s[12:13], v56, s38, v[12:13]
	global_load_dwordx4 v[56:59], v[56:57], off

.LBB0_1725:
	s_or_b64 exec, exec, s[18:19]
	s_and_b64 vcc, exec, s[12:13]
	s_cbranch_vccnz .LBB0_1727
	v_ashrrev_i32_e32 v9, 31, v8
	v_lshl_add_u64 v[40:41], v[8:9], 0, v[4:5]
	v_lshl_add_u64 v[40:41], v[40:41], 2, s[2:3]
	global_load_dword v44, v[40:41], off offset:64
	s_branch .LBB0_1728

.LBB0_1728:
	v_mov_b32_e32 v40, 0
	v_mov_b32_e32 v41, 0
	v_mov_b32_e32 v42, 0
	v_mov_b32_e32 v43, 0
	s_and_saveexec_b64 s[18:19], s[10:11]
	s_cbranch_execz .LBB0_1730
	v_add_u32_e32 v40, v8, v20
	v_ashrrev_i32_e32 v41, 31, v40
	v_lshlrev_b64 v[40:41], 12, v[40:41]
	v_lshl_add_u64 v[40:41], v[12:13], 0, v[40:41]
	global_load_dwordx4 v[40:43], v[40:41], off
.LBB0_1730:
	s_or_b64 exec, exec, s[18:19]
	s_and_b64 vcc, exec, s[12:13]
	s_cbranch_vccnz .LBB0_1732
	v_ashrrev_i32_e32 v9, 31, v8
	v_lshl_add_u64 v[48:49], v[8:9], 0, v[4:5]
	v_lshl_add_u64 v[48:49], v[48:49], 2, s[2:3]
	global_load_dword v52, v[48:49], off offset:128
	s_branch .LBB0_1733

.LBB0_1733:
	v_mov_b32_e32 v48, 0
	v_mov_b32_e32 v49, 0
	v_mov_b32_e32 v50, 0
	v_mov_b32_e32 v51, 0
	s_and_saveexec_b64 s[18:19], s[10:11]
	s_cbranch_execz .LBB0_1735
	v_add_u32_e32 v48, v8, v22
	v_ashrrev_i32_e32 v49, 31, v48
	v_lshlrev_b64 v[48:49], 12, v[48:49]
	v_lshl_add_u64 v[48:49], v[12:13], 0, v[48:49]
	global_load_dwordx4 v[48:51], v[48:49], off
.LBB0_1735:
	s_or_b64 exec, exec, s[18:19]
	s_and_b64 vcc, exec, s[12:13]
	s_cbranch_vccnz .LBB0_1737
	v_ashrrev_i32_e32 v9, 31, v8
	v_lshl_add_u64 v[56:57], v[8:9], 0, v[4:5]
	v_lshl_add_u64 v[56:57], v[56:57], 2, s[2:3]
	global_load_dword v60, v[56:57], off offset:192
	s_branch .LBB0_1738

.LBB0_1757:
	s_or_b64 exec, exec, s[20:21]
	s_and_b64 vcc, exec, s[12:13]
	s_cbranch_vccnz .LBB0_1759
	v_ashrrev_i32_e32 v9, 31, v8
	v_lshl_add_u64 v[40:41], v[8:9], 0, v[4:5]
	v_lshl_add_u64 v[40:41], v[40:41], 2, s[14:15]
	global_load_dword v44, v[40:41], off offset:64
	s_branch .LBB0_1760

.LBB0_1760:
	v_mov_b32_e32 v40, 0
	v_mov_b32_e32 v41, 0
	v_mov_b32_e32 v42, 0
	v_mov_b32_e32 v43, 0
	s_and_saveexec_b64 s[20:21], s[10:11]
	s_cbranch_execz .LBB0_1762
	v_add_u32_e32 v40, v8, v20
	v_ashrrev_i32_e32 v41, 31, v40
	v_lshlrev_b64 v[40:41], 12, v[40:41]
	v_lshl_add_u64 v[40:41], v[12:13], 0, v[40:41]
	global_load_dwordx4 v[40:43], v[40:41], off
.LBB0_1762:
	s_or_b64 exec, exec, s[20:21]
	s_and_b64 vcc, exec, s[12:13]
	s_cbranch_vccnz .LBB0_1764
	v_ashrrev_i32_e32 v9, 31, v8
	v_lshl_add_u64 v[48:49], v[8:9], 0, v[4:5]
	v_lshl_add_u64 v[48:49], v[48:49], 2, s[14:15]
	global_load_dword v52, v[48:49], off offset:128
	s_branch .LBB0_1765

.LBB0_1765:
	v_mov_b32_e32 v48, 0
	v_mov_b32_e32 v49, 0
	v_mov_b32_e32 v50, 0
	v_mov_b32_e32 v51, 0
	s_and_saveexec_b64 s[20:21], s[10:11]
	s_cbranch_execz .LBB0_1767
	v_add_u32_e32 v48, v8, v22
	v_ashrrev_i32_e32 v49, 31, v48
	v_lshlrev_b64 v[48:49], 12, v[48:49]
	v_lshl_add_u64 v[48:49], v[12:13], 0, v[48:49]
	global_load_dwordx4 v[48:51], v[48:49], off
.LBB0_1767:
	s_or_b64 exec, exec, s[20:21]
	s_and_b64 vcc, exec, s[12:13]
	s_cbranch_vccnz .LBB0_1769
	v_ashrrev_i32_e32 v9, 31, v8
	v_lshl_add_u64 v[56:57], v[8:9], 0, v[4:5]
	v_lshl_add_u64 v[56:57], v[56:57], 2, s[14:15]
	global_load_dword v60, v[56:57], off offset:192
	s_branch .LBB0_1770

.LBB0_1821:
	s_or_b64 exec, exec, s[16:17]
	s_and_b64 vcc, exec, s[10:11]
	s_cbranch_vccnz .LBB0_1823
	v_ashrrev_i32_e32 v9, 31, v8
	v_lshl_add_u64 v[40:41], v[8:9], 0, v[4:5]
	v_lshl_add_u64 v[40:41], v[40:41], 2, s[12:13]
	global_load_dword v44, v[40:41], off offset:64
	s_branch .LBB0_1824

.LBB0_1824:
	v_mov_b32_e32 v40, 0
	v_mov_b32_e32 v41, 0
	v_mov_b32_e32 v42, 0
	v_mov_b32_e32 v43, 0
	s_and_saveexec_b64 s[16:17], s[8:9]
	s_cbranch_execz .LBB0_1826
	v_add_u32_e32 v40, v8, v20
	v_ashrrev_i32_e32 v41, 31, v40
	v_lshlrev_b64 v[40:41], 12, v[40:41]
	v_lshl_add_u64 v[40:41], v[12:13], 0, v[40:41]
	global_load_dwordx4 v[40:43], v[40:41], off
.LBB0_1826:
	s_or_b64 exec, exec, s[16:17]
	s_and_b64 vcc, exec, s[10:11]
	s_cbranch_vccnz .LBB0_1828
	v_ashrrev_i32_e32 v9, 31, v8
	v_lshl_add_u64 v[48:49], v[8:9], 0, v[4:5]
	v_lshl_add_u64 v[48:49], v[48:49], 2, s[12:13]
	global_load_dword v52, v[48:49], off offset:128
	s_branch .LBB0_1829

.LBB0_1829:
	v_mov_b32_e32 v48, 0
	v_mov_b32_e32 v49, 0
	v_mov_b32_e32 v50, 0
	v_mov_b32_e32 v51, 0
	s_and_saveexec_b64 s[16:17], s[8:9]
	s_cbranch_execz .LBB0_1831
	v_add_u32_e32 v48, v8, v22
	v_ashrrev_i32_e32 v49, 31, v48
	v_lshlrev_b64 v[48:49], 12, v[48:49]
	v_lshl_add_u64 v[48:49], v[12:13], 0, v[48:49]
	global_load_dwordx4 v[48:51], v[48:49], off
.LBB0_1831:
	s_or_b64 exec, exec, s[16:17]
	s_and_b64 vcc, exec, s[10:11]
	s_cbranch_vccnz .LBB0_1833
	v_ashrrev_i32_e32 v9, 31, v8
	v_lshl_add_u64 v[56:57], v[8:9], 0, v[4:5]
	v_lshl_add_u64 v[56:57], v[56:57], 2, s[12:13]
	global_load_dword v60, v[56:57], off offset:192
	s_branch .LBB0_1834

.LBB0_1853:
	s_or_b64 exec, exec, s[18:19]
	s_and_b64 vcc, exec, s[10:11]
	s_cbranch_vccnz .LBB0_1855
	v_ashrrev_i32_e32 v9, 31, v8
	v_lshl_add_u64 v[40:41], v[8:9], 0, v[4:5]
	v_lshl_add_u64 v[40:41], v[40:41], 2, s[2:3]
	global_load_dword v44, v[40:41], off offset:64
	s_branch .LBB0_1856

.LBB0_1856:
	v_mov_b32_e32 v40, 0
	v_mov_b32_e32 v41, 0
	v_mov_b32_e32 v42, 0
	v_mov_b32_e32 v43, 0
	s_and_saveexec_b64 s[18:19], s[8:9]
	s_cbranch_execz .LBB0_1858
	v_add_u32_e32 v40, v8, v20
	v_ashrrev_i32_e32 v41, 31, v40
	v_lshlrev_b64 v[40:41], 12, v[40:41]
	v_lshl_add_u64 v[40:41], v[12:13], 0, v[40:41]
	global_load_dwordx4 v[40:43], v[40:41], off
.LBB0_1858:
	s_or_b64 exec, exec, s[18:19]
	s_and_b64 vcc, exec, s[10:11]
	s_cbranch_vccnz .LBB0_1860
	v_ashrrev_i32_e32 v9, 31, v8
	v_lshl_add_u64 v[48:49], v[8:9], 0, v[4:5]
	v_lshl_add_u64 v[48:49], v[48:49], 2, s[2:3]
	global_load_dword v52, v[48:49], off offset:128
	s_branch .LBB0_1861

.LBB0_1861:
	v_mov_b32_e32 v48, 0
	v_mov_b32_e32 v49, 0
	v_mov_b32_e32 v50, 0
	v_mov_b32_e32 v51, 0
	s_and_saveexec_b64 s[18:19], s[8:9]
	s_cbranch_execz .LBB0_1863
	v_add_u32_e32 v48, v8, v22
	v_ashrrev_i32_e32 v49, 31, v48
	v_lshlrev_b64 v[48:49], 12, v[48:49]
	v_lshl_add_u64 v[48:49], v[12:13], 0, v[48:49]
	global_load_dwordx4 v[48:51], v[48:49], off
.LBB0_1863:
	s_or_b64 exec, exec, s[18:19]
	s_and_b64 vcc, exec, s[10:11]
	s_cbranch_vccnz .LBB0_1865
	v_ashrrev_i32_e32 v9, 31, v8
	v_lshl_add_u64 v[56:57], v[8:9], 0, v[4:5]
	v_lshl_add_u64 v[56:57], v[56:57], 2, s[2:3]
	global_load_dword v60, v[56:57], off offset:192
	s_branch .LBB0_1866

.LBB0_1933:
	s_or_b64 exec, exec, s[18:19]
	s_and_b64 vcc, exec, s[10:11]
	s_cbranch_vccnz .LBB0_1935
	v_ashrrev_i32_e32 v9, 31, v8
	v_lshl_add_u64 v[40:41], v[8:9], 0, v[4:5]
	v_lshl_add_u64 v[40:41], v[40:41], 2, s[12:13]
	global_load_dword v44, v[40:41], off offset:64
	s_branch .LBB0_1936

.LBB0_1936:
	v_mov_b32_e32 v40, 0
	v_mov_b32_e32 v41, 0
	v_mov_b32_e32 v42, 0
	v_mov_b32_e32 v43, 0
	s_and_saveexec_b64 s[18:19], s[8:9]
	s_cbranch_execz .LBB0_1938
	v_add_u32_e32 v40, v8, v20
	v_ashrrev_i32_e32 v41, 31, v40
	v_lshlrev_b64 v[40:41], 14, v[40:41]
	v_lshl_add_u64 v[40:41], v[12:13], 0, v[40:41]
	global_load_dwordx4 v[40:43], v[40:41], off
.LBB0_1938:
	s_or_b64 exec, exec, s[18:19]
	s_and_b64 vcc, exec, s[10:11]
	s_cbranch_vccnz .LBB0_1940
	v_ashrrev_i32_e32 v9, 31, v8
	v_lshl_add_u64 v[48:49], v[8:9], 0, v[4:5]
	v_lshl_add_u64 v[48:49], v[48:49], 2, s[12:13]
	global_load_dword v52, v[48:49], off offset:128
	s_branch .LBB0_1941

.LBB0_1941:
	v_mov_b32_e32 v48, 0
	v_mov_b32_e32 v49, 0
	v_mov_b32_e32 v50, 0
	v_mov_b32_e32 v51, 0
	s_and_saveexec_b64 s[18:19], s[8:9]
	s_cbranch_execz .LBB0_1943
	v_add_u32_e32 v48, v8, v22
	v_ashrrev_i32_e32 v49, 31, v48
	v_lshlrev_b64 v[48:49], 14, v[48:49]
	v_lshl_add_u64 v[48:49], v[12:13], 0, v[48:49]
	global_load_dwordx4 v[48:51], v[48:49], off
.LBB0_1943:
	s_or_b64 exec, exec, s[18:19]
	s_and_b64 vcc, exec, s[10:11]
	s_cbranch_vccnz .LBB0_1945
	v_ashrrev_i32_e32 v9, 31, v8
	v_lshl_add_u64 v[56:57], v[8:9], 0, v[4:5]
	v_lshl_add_u64 v[56:57], v[56:57], 2, s[12:13]
	global_load_dword v60, v[56:57], off offset:192
	s_branch .LBB0_1946
